# attention: the 16 SGPR restore readlanes run once per item instead of once per key tile (nothing in the key-tile loop clobbers them any more)
# speedup vs baseline: 1.0066x; 1.0011x over previous
.Lattn0_ld9:
	s_or_b64 exec, exec, s[0:1]
	s_waitcnt vmcnt(0)
	s_barrier
	ds_write_b128 v189, v[10:13]
	ds_write_b128 v190, v[14:17]
	ds_write_b128 v191, v[18:21]
	ds_write_b128 v192, v[22:25]
	ds_write_b128 v193, v[26:29]
	ds_write_b16 v180, v30 offset:46080
	ds_write_b16_d16_hi v180, v30 offset:46736
	ds_write_b16 v180, v31 offset:47392
	ds_write_b16_d16_hi v180, v31 offset:48048
	ds_write_b16 v180, v32 offset:48704
	ds_write_b16_d16_hi v180, v32 offset:49360
	ds_write_b16 v180, v33 offset:50016
	ds_write_b16_d16_hi v180, v33 offset:50672
	ds_write_b16 v180, v34 offset:46208
	ds_write_b16_d16_hi v180, v34 offset:46864
	ds_write_b16 v180, v35 offset:47520
	ds_write_b16_d16_hi v180, v35 offset:48176
	ds_write_b16 v180, v36 offset:48832
	ds_write_b16_d16_hi v180, v36 offset:49488
	ds_write_b16 v180, v37 offset:50144
	ds_write_b16_d16_hi v180, v37 offset:50800
	ds_write_b16 v180, v38 offset:46336
	ds_write_b16_d16_hi v180, v38 offset:46992
	ds_write_b16 v180, v39 offset:47648
	ds_write_b16_d16_hi v180, v39 offset:48304
	ds_write_b16 v180, v40 offset:48960
	ds_write_b16_d16_hi v180, v40 offset:49616
	ds_write_b16 v180, v41 offset:50272
	ds_write_b16_d16_hi v180, v41 offset:50928
	ds_write_b16 v180, v42 offset:46464
	ds_write_b16_d16_hi v180, v42 offset:47120
	ds_write_b16 v180, v43 offset:47776
	ds_write_b16_d16_hi v180, v43 offset:48432
	ds_write_b16 v180, v44 offset:49088
	ds_write_b16_d16_hi v180, v44 offset:49744
	ds_write_b16 v180, v45 offset:50400
	ds_write_b16_d16_hi v180, v45 offset:51056
	ds_write_b16 v180, v46 offset:46592
	ds_write_b16_d16_hi v180, v46 offset:47248
	ds_write_b16 v180, v47 offset:47904
	ds_write_b16_d16_hi v180, v47 offset:48560
	ds_write_b16 v180, v48 offset:49216
	ds_write_b16_d16_hi v180, v48 offset:49872
	ds_write_b16 v180, v49 offset:50528
	ds_write_b16_d16_hi v180, v49 offset:51184
	v_mov_b32_e32 v14, v0
	v_mov_b32_e32 v15, v0
	v_mov_b32_e32 v1, v0
	v_mov_b32_e32 v2, v0
	v_mov_b32_e32 v3, v0
	v_mov_b32_e32 v4, v0
	v_mov_b32_e32 v5, v0
	v_mov_b32_e32 v6, v0
	v_mov_b32_e32 v7, v0
	v_mov_b32_e32 v8, v0
	v_mov_b32_e32 v9, v0
	v_mov_b32_e32 v10, v0
	v_mov_b32_e32 v11, v0
	v_mov_b32_e32 v12, v0
	v_mov_b32_e32 v13, v0
	v_mov_b64_e32 v[64:65], v[14:15]
	v_mov_b64_e32 v[32:33], v[14:15]
	v_mov_b64_e32 v[48:49], v[14:15]
	s_and_b32 s0, s2, 0xffffffc0
	v_mov_b64_e32 v[62:63], v[12:13]
	v_mov_b64_e32 v[60:61], v[10:11]
	v_mov_b64_e32 v[58:59], v[8:9]
	v_mov_b64_e32 v[56:57], v[6:7]
	v_mov_b64_e32 v[54:55], v[4:5]
	v_mov_b64_e32 v[52:53], v[2:3]
	v_mov_b64_e32 v[50:51], v[0:1]
	v_mov_b64_e32 v[30:31], v[12:13]
	v_mov_b64_e32 v[28:29], v[10:11]
	v_mov_b64_e32 v[26:27], v[8:9]
	v_mov_b64_e32 v[24:25], v[6:7]
	v_mov_b64_e32 v[22:23], v[4:5]
	v_mov_b64_e32 v[20:21], v[2:3]
	v_mov_b64_e32 v[18:19], v[0:1]
	v_mov_b64_e32 v[46:47], v[12:13]
	v_mov_b64_e32 v[44:45], v[10:11]
	v_mov_b64_e32 v[42:43], v[8:9]
	v_mov_b64_e32 v[40:41], v[6:7]
	v_mov_b64_e32 v[38:39], v[4:5]
	v_mov_b64_e32 v[36:37], v[2:3]
	v_mov_b64_e32 v[34:35], v[0:1]
	v_mov_b64_e32 v[16:17], v[14:15]
	s_sub_i32 s72, s0, s4
	v_mov_b32_e32 v199, 1.0
	v_mov_b32_e32 v196, v187
	v_mov_b32_e32 v197, v186
	v_mov_b32_e32 v198, v185
	v_mov_b64_e32 v[14:15], v[12:13]
	v_mov_b64_e32 v[12:13], v[10:11]
	v_mov_b64_e32 v[10:11], v[8:9]
	v_mov_b64_e32 v[8:9], v[6:7]
	v_mov_b64_e32 v[6:7], v[4:5]
	v_mov_b64_e32 v[4:5], v[2:3]
	v_mov_b64_e32 v[2:3], v[0:1]
	v_mov_b32_e32 v1, 1.0
	v_mov_b32_e32 v200, v202
	s_mov_b32 s78, 0
	s_waitcnt lgkmcnt(0)
	s_barrier
	v_readlane_b32 s48, v254, 0
	v_readlane_b32 s49, v254, 1
	v_readlane_b32 s50, v254, 2
	v_readlane_b32 s51, v254, 3
	v_readlane_b32 s58, v254, 10
	v_readlane_b32 s59, v254, 11
	v_readlane_b32 s52, v254, 4
	v_readlane_b32 s53, v254, 5
	v_readlane_b32 s54, v254, 6
	v_readlane_b32 s55, v254, 7
	v_readlane_b32 s56, v254, 8
	v_readlane_b32 s57, v254, 9
	v_readlane_b32 s60, v254, 12
	v_readlane_b32 s61, v254, 13
	v_readlane_b32 s62, v254, 14
	v_readlane_b32 s63, v254, 15

.LBB0_634:
	s_xor_b64 s[0:1], s[94:95], -1
	s_andn2_b64 vcc, exec, s[0:1]
	s_mov_b64 s[0:1], -1
	s_cbranch_vccnz .LBB0_636
	s_mov_b32 s0, 0xf149f2ca
	v_max3_f32 v101, v82, s0, v83
	v_max3_f32 v101, v101, v84, v85
	v_max3_f32 v101, v101, v86, v87
	v_max3_f32 v101, v101, v88, v89
	v_max3_f32 v101, v101, v90, v91
	v_max3_f32 v101, v101, v92, v93
	v_max3_f32 v101, v101, v94, v95
	v_max3_f32 v101, v101, v96, v97
	v_max3_f32 v101, v101, v66, v67
	v_max3_f32 v101, v101, v68, v69
	v_max3_f32 v101, v101, v70, v71
	v_max3_f32 v101, v101, v72, v73
	v_max3_f32 v101, v101, v74, v75
	v_max3_f32 v101, v101, v76, v77
	v_max3_f32 v101, v101, v78, v79
	v_max3_f32 v101, v101, v80, v81
	s_mov_b64 s[0:1], 0

.Lattn1_ld9:
	s_or_b64 exec, exec, s[0:1]
	s_waitcnt vmcnt(0)
	s_barrier
	ds_write_b128 v189, v[10:13]
	ds_write_b128 v190, v[14:17]
	ds_write_b128 v191, v[18:21]
	ds_write_b128 v192, v[22:25]
	ds_write_b128 v193, v[26:29]
	ds_write_b16 v180, v30 offset:46080
	ds_write_b16_d16_hi v180, v30 offset:46736
	ds_write_b16 v180, v31 offset:47392
	ds_write_b16_d16_hi v180, v31 offset:48048
	ds_write_b16 v180, v32 offset:48704
	ds_write_b16_d16_hi v180, v32 offset:49360
	ds_write_b16 v180, v33 offset:50016
	ds_write_b16_d16_hi v180, v33 offset:50672
	ds_write_b16 v180, v34 offset:46208
	ds_write_b16_d16_hi v180, v34 offset:46864
	ds_write_b16 v180, v35 offset:47520
	ds_write_b16_d16_hi v180, v35 offset:48176
	ds_write_b16 v180, v36 offset:48832
	ds_write_b16_d16_hi v180, v36 offset:49488
	ds_write_b16 v180, v37 offset:50144
	ds_write_b16_d16_hi v180, v37 offset:50800
	ds_write_b16 v180, v38 offset:46336
	ds_write_b16_d16_hi v180, v38 offset:46992
	ds_write_b16 v180, v39 offset:47648
	ds_write_b16_d16_hi v180, v39 offset:48304
	ds_write_b16 v180, v40 offset:48960
	ds_write_b16_d16_hi v180, v40 offset:49616
	ds_write_b16 v180, v41 offset:50272
	ds_write_b16_d16_hi v180, v41 offset:50928
	ds_write_b16 v180, v42 offset:46464
	ds_write_b16_d16_hi v180, v42 offset:47120
	ds_write_b16 v180, v43 offset:47776
	ds_write_b16_d16_hi v180, v43 offset:48432
	ds_write_b16 v180, v44 offset:49088
	ds_write_b16_d16_hi v180, v44 offset:49744
	ds_write_b16 v180, v45 offset:50400
	ds_write_b16_d16_hi v180, v45 offset:51056
	ds_write_b16 v180, v46 offset:46592
	ds_write_b16_d16_hi v180, v46 offset:47248
	ds_write_b16 v180, v47 offset:47904
	ds_write_b16_d16_hi v180, v47 offset:48560
	ds_write_b16 v180, v48 offset:49216
	ds_write_b16_d16_hi v180, v48 offset:49872
	ds_write_b16 v180, v49 offset:50528
	ds_write_b16_d16_hi v180, v49 offset:51184
	v_mov_b32_e32 v14, v0
	v_mov_b32_e32 v15, v0
	v_mov_b32_e32 v1, v0
	v_mov_b32_e32 v2, v0
	v_mov_b32_e32 v3, v0
	v_mov_b32_e32 v4, v0
	v_mov_b32_e32 v5, v0
	v_mov_b32_e32 v6, v0
	v_mov_b32_e32 v7, v0
	v_mov_b32_e32 v8, v0
	v_mov_b32_e32 v9, v0
	v_mov_b32_e32 v10, v0
	v_mov_b32_e32 v11, v0
	v_mov_b32_e32 v12, v0
	v_mov_b32_e32 v13, v0
	v_mov_b64_e32 v[64:65], v[14:15]
	v_mov_b64_e32 v[32:33], v[14:15]
	v_mov_b64_e32 v[48:49], v[14:15]
	s_and_b32 s0, s95, 0xffffffc0
	v_mov_b64_e32 v[62:63], v[12:13]
	v_mov_b64_e32 v[60:61], v[10:11]
	v_mov_b64_e32 v[58:59], v[8:9]
	v_mov_b64_e32 v[56:57], v[6:7]
	v_mov_b64_e32 v[54:55], v[4:5]
	v_mov_b64_e32 v[52:53], v[2:3]
	v_mov_b64_e32 v[50:51], v[0:1]
	v_mov_b64_e32 v[30:31], v[12:13]
	v_mov_b64_e32 v[28:29], v[10:11]
	v_mov_b64_e32 v[26:27], v[8:9]
	v_mov_b64_e32 v[24:25], v[6:7]
	v_mov_b64_e32 v[22:23], v[4:5]
	v_mov_b64_e32 v[20:21], v[2:3]
	v_mov_b64_e32 v[18:19], v[0:1]
	v_mov_b64_e32 v[46:47], v[12:13]
	v_mov_b64_e32 v[44:45], v[10:11]
	v_mov_b64_e32 v[42:43], v[8:9]
	v_mov_b64_e32 v[40:41], v[6:7]
	v_mov_b64_e32 v[38:39], v[4:5]
	v_mov_b64_e32 v[36:37], v[2:3]
	v_mov_b64_e32 v[34:35], v[0:1]
	v_mov_b64_e32 v[16:17], v[14:15]
	s_sub_i32 s72, s0, s4
	v_mov_b32_e32 v199, 1.0
	v_mov_b32_e32 v196, v187
	v_mov_b32_e32 v197, v186
	v_mov_b32_e32 v198, v185
	v_mov_b64_e32 v[14:15], v[12:13]
	v_mov_b64_e32 v[12:13], v[10:11]
	v_mov_b64_e32 v[10:11], v[8:9]
	v_mov_b64_e32 v[8:9], v[6:7]
	v_mov_b64_e32 v[6:7], v[4:5]
	v_mov_b64_e32 v[4:5], v[2:3]
	v_mov_b64_e32 v[2:3], v[0:1]
	v_mov_b32_e32 v1, 1.0
	v_mov_b32_e32 v200, v202
	s_mov_b32 s94, 0
	s_waitcnt lgkmcnt(0)
	s_barrier
	v_readlane_b32 s48, v254, 0
	v_readlane_b32 s49, v254, 1
	v_readlane_b32 s50, v254, 2
	v_readlane_b32 s51, v254, 3
	v_readlane_b32 s54, v254, 6
	v_readlane_b32 s55, v254, 7
	v_readlane_b32 s58, v254, 10
	v_readlane_b32 s59, v254, 11
	v_readlane_b32 s52, v254, 4
	v_readlane_b32 s53, v254, 5
	v_readlane_b32 s56, v254, 8
	v_readlane_b32 s57, v254, 9
	v_readlane_b32 s60, v254, 12
	v_readlane_b32 s61, v254, 13
	v_readlane_b32 s62, v254, 14
	v_readlane_b32 s63, v254, 15

.LBB0_2216:
	s_xor_b64 s[0:1], s[92:93], -1
	s_andn2_b64 vcc, exec, s[0:1]
	s_mov_b64 s[0:1], -1
	s_cbranch_vccnz .LBB0_2218
	s_mov_b32 s0, 0xf149f2ca
	v_max3_f32 v101, v82, s0, v83
	v_max3_f32 v101, v101, v84, v85
	v_max3_f32 v101, v101, v86, v87
	v_max3_f32 v101, v101, v88, v89
	v_max3_f32 v101, v101, v90, v91
	v_max3_f32 v101, v101, v92, v93
	v_max3_f32 v101, v101, v94, v95
	v_max3_f32 v101, v101, v96, v97
	v_max3_f32 v101, v101, v66, v67
	v_max3_f32 v101, v101, v68, v69
	v_max3_f32 v101, v101, v70, v71
	v_max3_f32 v101, v101, v72, v73
	v_max3_f32 v101, v101, v74, v75
	v_max3_f32 v101, v101, v76, v77
	v_max3_f32 v101, v101, v78, v79
	v_max3_f32 v101, v101, v80, v81
	s_mov_b64 s[0:1], 0
